# decode P.c products: operand reads issued four 16-key steps ahead into rotating operand sets with counted waits
# speedup vs baseline: 1.0054x; 1.0054x over previous
.LBB0_1570:
	v_mov_b32_e32 v5, v229
	v_mov_b32_e32 v8, s80
	v_and_b32_e32 v6, 31, v5
	v_cmp_eq_u32_e32 vcc, 0, v6
	v_mad_u32_u24 v6, v6, s88, v8
	v_ashrrev_i32_e32 v8, 2, v5
	v_and_b32_e32 v13, -8, v8
	v_bfe_u32 v12, v5, 2, 2
	v_and_b32_e32 v8, 16, v5
	v_lshlrev_b32_e32 v5, 2, v5
	v_and_b32_e32 v5, 12, v5
	v_or3_b32 v5, v8, v5, s30
	v_lshlrev_b32_e32 v14, 1, v5
	v_lshl_add_u32 v5, v13, 1, v6
	ds_read_b128 v[8:11], v5
	v_or_b32_e32 v5, v13, v12
	v_mul_lo_u32 v5, v5, s52
	v_add3_u32 v5, 0, v5, v14
	ds_read_b64_tr_b16 v[98:99], v5
	ds_read_b64_tr_b16 v[100:101], v5 offset:2112
	v_add_u32_e32 v15, 16, v13
	v_lshl_add_u32 v102, v15, 1, v6
	ds_read_b128 v[102:105], v102
	v_or_b32_e32 v15, v15, v12
	v_mul_lo_u32 v15, v15, s52
	v_add3_u32 v15, 0, v15, v14
	ds_read_b64_tr_b16 v[106:107], v15
	ds_read_b64_tr_b16 v[108:109], v15 offset:2112
	v_add_u32_e32 v15, 32, v13
	v_lshl_add_u32 v110, v15, 1, v6
	ds_read_b128 v[110:113], v110
	v_or_b32_e32 v15, v15, v12
	v_mul_lo_u32 v15, v15, s52
	v_add3_u32 v15, 0, v15, v14
	ds_read_b64_tr_b16 v[114:115], v15
	ds_read_b64_tr_b16 v[116:117], v15 offset:2112
	v_add_u32_e32 v15, 48, v13
	v_lshl_add_u32 v118, v15, 1, v6
	ds_read_b128 v[118:121], v118
	v_or_b32_e32 v15, v15, v12
	v_mul_lo_u32 v15, v15, s52
	v_add3_u32 v15, 0, v15, v14
	ds_read_b64_tr_b16 v[122:123], v15
	ds_read_b64_tr_b16 v[124:125], v15 offset:2112
	s_waitcnt lgkmcnt(9)
	v_mfma_f32_32x32x16_bf16 v[82:97], v[8:11], v[98:101], v[82:97]
	v_readlane_b32 s0, v253, 58
	v_readlane_b32 s1, v253, 59
	v_cndmask_b32_e32 v2, 0, v242, vcc
	v_mov_b32_e32 v3, v2
	v_cndmask_b32_e64 v15, 0, 1, s[0:1]
	v_mov_b32_e32 v4, v2
	v_mov_b32_e32 v5, v2
	v_cmp_ne_u32_e64 s[10:11], 1, v15
	s_andn2_b64 vcc, exec, s[0:1]
	s_cbranch_vccnz .LBB0_1572
	v_mfma_f32_32x32x16_bf16 v[18:33], v[8:11], v[2:5], v[18:33]
.LBB0_1572:
	v_add_u32_e32 v15, 64, v13
	v_lshl_add_u32 v8, v15, 1, v6
	ds_read_b128 v[8:11], v8
	v_or_b32_e32 v15, v15, v12
	v_mul_lo_u32 v15, v15, s52
	v_add3_u32 v15, 0, v15, v14
	ds_read_b64_tr_b16 v[98:99], v15
	ds_read_b64_tr_b16 v[100:101], v15 offset:2112
	v_cndmask_b32_e64 v15, 0, 1, s[38:39]
	v_cmp_ne_u32_e64 s[12:13], 1, v15
	s_andn2_b64 vcc, exec, s[38:39]
	s_waitcnt lgkmcnt(9)
	v_mfma_f32_32x32x16_bf16 v[82:97], v[102:105], v[106:109], v[82:97]
	s_cbranch_vccnz .LBB0_1574
	v_mfma_f32_32x32x16_bf16 v[18:33], v[102:105], v[2:5], v[18:33]
.LBB0_1574:
	v_add_u32_e32 v15, 80, v13
	v_lshl_add_u32 v102, v15, 1, v6
	ds_read_b128 v[102:105], v102
	v_or_b32_e32 v15, v15, v12
	v_mul_lo_u32 v15, v15, s52
	v_add3_u32 v15, 0, v15, v14
	ds_read_b64_tr_b16 v[106:107], v15
	ds_read_b64_tr_b16 v[108:109], v15 offset:2112
	v_cndmask_b32_e64 v15, 0, 1, s[40:41]
	v_cmp_ne_u32_e64 s[14:15], 1, v15
	s_andn2_b64 vcc, exec, s[40:41]
	s_waitcnt lgkmcnt(9)
	v_mfma_f32_32x32x16_bf16 v[82:97], v[110:113], v[114:117], v[82:97]
	s_cbranch_vccnz .LBB0_1576
	v_mfma_f32_32x32x16_bf16 v[18:33], v[110:113], v[2:5], v[18:33]
.LBB0_1576:
	v_add_u32_e32 v15, 96, v13
	v_lshl_add_u32 v110, v15, 1, v6
	ds_read_b128 v[110:113], v110
	v_or_b32_e32 v15, v15, v12
	v_mul_lo_u32 v15, v15, s52
	v_add3_u32 v15, 0, v15, v14
	ds_read_b64_tr_b16 v[114:115], v15
	ds_read_b64_tr_b16 v[116:117], v15 offset:2112
	v_cndmask_b32_e64 v15, 0, 1, s[48:49]
	v_cmp_ne_u32_e64 s[16:17], 1, v15
	s_andn2_b64 vcc, exec, s[48:49]
	s_waitcnt lgkmcnt(9)
	v_mfma_f32_32x32x16_bf16 v[82:97], v[118:121], v[122:125], v[82:97]
	s_cbranch_vccnz .LBB0_1578
	v_mfma_f32_32x32x16_bf16 v[18:33], v[118:121], v[2:5], v[18:33]
.LBB0_1578:
	v_add_u32_e32 v15, 112, v13
	v_lshl_add_u32 v118, v15, 1, v6
	ds_read_b128 v[118:121], v118
	v_or_b32_e32 v15, v15, v12
	v_mul_lo_u32 v15, v15, s52
	v_add3_u32 v15, 0, v15, v14
	ds_read_b64_tr_b16 v[122:123], v15
	ds_read_b64_tr_b16 v[124:125], v15 offset:2112
	v_cndmask_b32_e64 v15, 0, 1, s[60:61]
	v_cmp_ne_u32_e64 s[18:19], 1, v15
	s_andn2_b64 vcc, exec, s[60:61]
	s_waitcnt lgkmcnt(9)
	v_mfma_f32_32x32x16_bf16 v[82:97], v[8:11], v[98:101], v[82:97]
	s_cbranch_vccnz .LBB0_1580
	v_mfma_f32_32x32x16_bf16 v[18:33], v[8:11], v[2:5], v[18:33]
.LBB0_1580:
	v_cndmask_b32_e64 v15, 0, 1, s[62:63]
	v_cmp_ne_u32_e64 s[20:21], 1, v15
	s_andn2_b64 vcc, exec, s[62:63]
	s_waitcnt lgkmcnt(6)
	v_mfma_f32_32x32x16_bf16 v[82:97], v[102:105], v[106:109], v[82:97]
	s_cbranch_vccnz .LBB0_1582
	v_mfma_f32_32x32x16_bf16 v[18:33], v[102:105], v[2:5], v[18:33]
.LBB0_1582:
	v_cndmask_b32_e64 v15, 0, 1, s[72:73]
	v_cmp_ne_u32_e64 s[22:23], 1, v15
	s_andn2_b64 vcc, exec, s[72:73]
	s_waitcnt lgkmcnt(3)
	v_mfma_f32_32x32x16_bf16 v[82:97], v[110:113], v[114:117], v[82:97]
	s_cbranch_vccnz .LBB0_1584
	v_mfma_f32_32x32x16_bf16 v[18:33], v[110:113], v[2:5], v[18:33]
.LBB0_1584:
	v_cndmask_b32_e64 v6, 0, 1, s[74:75]
	v_cmp_ne_u32_e64 s[24:25], 1, v6
	s_andn2_b64 vcc, exec, s[74:75]
	s_waitcnt lgkmcnt(0)
	v_mfma_f32_32x32x16_bf16 v[82:97], v[118:121], v[122:125], v[82:97]
	s_cbranch_vccnz .LBB0_1586
	v_mfma_f32_32x32x16_bf16 v[18:33], v[118:121], v[2:5], v[18:33]

.LBB0_1600:
	v_mov_b32_e32 v3, v229
	s_add_i32 s91, 0, 0x25600
	v_mov_b32_e32 v5, s91
	v_and_b32_e32 v4, 31, v3
	v_cmp_eq_u32_e32 vcc, 1, v4
	v_mad_u32_u24 v6, v4, s88, v5
	v_ashrrev_i32_e32 v4, 2, v3
	v_and_b32_e32 v13, -8, v4
	v_bfe_u32 v12, v3, 2, 2
	v_and_b32_e32 v4, 16, v3
	v_lshlrev_b32_e32 v3, 2, v3
	v_and_b32_e32 v3, 12, v3
	v_or3_b32 v3, v4, v3, s30
	v_lshlrev_b32_e32 v14, 1, v3
	v_lshl_add_u32 v3, v13, 1, v6
	ds_read_b128 v[8:11], v3
	v_or_b32_e32 v3, v13, v12
	v_mul_lo_u32 v3, v3, s52
	v_add3_u32 v3, 0, v3, v14
	ds_read_b64_tr_b16 v[98:99], v3
	ds_read_b64_tr_b16 v[100:101], v3 offset:2112
	v_add_u32_e32 v15, 16, v13
	v_lshl_add_u32 v102, v15, 1, v6
	ds_read_b128 v[102:105], v102
	v_or_b32_e32 v15, v15, v12
	v_mul_lo_u32 v15, v15, s52
	v_add3_u32 v15, 0, v15, v14
	ds_read_b64_tr_b16 v[106:107], v15
	ds_read_b64_tr_b16 v[108:109], v15 offset:2112
	v_add_u32_e32 v15, 32, v13
	v_lshl_add_u32 v110, v15, 1, v6
	ds_read_b128 v[110:113], v110
	v_or_b32_e32 v15, v15, v12
	v_mul_lo_u32 v15, v15, s52
	v_add3_u32 v15, 0, v15, v14
	ds_read_b64_tr_b16 v[114:115], v15
	ds_read_b64_tr_b16 v[116:117], v15 offset:2112
	v_add_u32_e32 v15, 48, v13
	v_lshl_add_u32 v118, v15, 1, v6
	ds_read_b128 v[118:121], v118
	v_or_b32_e32 v15, v15, v12
	v_mul_lo_u32 v15, v15, s52
	v_add3_u32 v15, 0, v15, v14
	ds_read_b64_tr_b16 v[122:123], v15
	ds_read_b64_tr_b16 v[124:125], v15 offset:2112
	s_waitcnt lgkmcnt(9)
	v_mfma_f32_32x32x16_bf16 v[66:81], v[8:11], v[98:101], v[66:81]
	v_cndmask_b32_e32 v2, 0, v242, vcc
	v_mov_b32_e32 v3, v2
	v_mov_b32_e32 v4, v2
	v_mov_b32_e32 v5, v2
	s_and_b64 vcc, exec, s[10:11]
	s_cbranch_vccnz .LBB0_1602
	v_mfma_f32_32x32x16_bf16 v[18:33], v[8:11], v[2:5], v[18:33]
.LBB0_1602:
	v_add_u32_e32 v15, 64, v13
	v_lshl_add_u32 v8, v15, 1, v6
	ds_read_b128 v[8:11], v8
	v_or_b32_e32 v15, v15, v12
	v_mul_lo_u32 v15, v15, s52
	v_add3_u32 v15, 0, v15, v14
	ds_read_b64_tr_b16 v[98:99], v15
	ds_read_b64_tr_b16 v[100:101], v15 offset:2112
	s_and_b64 vcc, exec, s[12:13]
	s_waitcnt lgkmcnt(9)
	v_mfma_f32_32x32x16_bf16 v[66:81], v[102:105], v[106:109], v[66:81]
	s_cbranch_vccnz .LBB0_1604
	v_mfma_f32_32x32x16_bf16 v[18:33], v[102:105], v[2:5], v[18:33]
.LBB0_1604:
	v_add_u32_e32 v15, 80, v13
	v_lshl_add_u32 v102, v15, 1, v6
	ds_read_b128 v[102:105], v102
	v_or_b32_e32 v15, v15, v12
	v_mul_lo_u32 v15, v15, s52
	v_add3_u32 v15, 0, v15, v14
	ds_read_b64_tr_b16 v[106:107], v15
	ds_read_b64_tr_b16 v[108:109], v15 offset:2112
	s_and_b64 vcc, exec, s[14:15]
	s_waitcnt lgkmcnt(9)
	v_mfma_f32_32x32x16_bf16 v[66:81], v[110:113], v[114:117], v[66:81]
	s_cbranch_vccnz .LBB0_1606
	v_mfma_f32_32x32x16_bf16 v[18:33], v[110:113], v[2:5], v[18:33]
.LBB0_1606:
	v_add_u32_e32 v15, 96, v13
	v_lshl_add_u32 v110, v15, 1, v6
	ds_read_b128 v[110:113], v110
	v_or_b32_e32 v15, v15, v12
	v_mul_lo_u32 v15, v15, s52
	v_add3_u32 v15, 0, v15, v14
	ds_read_b64_tr_b16 v[114:115], v15
	ds_read_b64_tr_b16 v[116:117], v15 offset:2112
	s_and_b64 vcc, exec, s[16:17]
	s_waitcnt lgkmcnt(9)
	v_mfma_f32_32x32x16_bf16 v[66:81], v[118:121], v[122:125], v[66:81]
	s_cbranch_vccnz .LBB0_1608
	v_mfma_f32_32x32x16_bf16 v[18:33], v[118:121], v[2:5], v[18:33]
.LBB0_1608:
	v_add_u32_e32 v15, 112, v13
	v_lshl_add_u32 v118, v15, 1, v6
	ds_read_b128 v[118:121], v118
	v_or_b32_e32 v15, v15, v12
	v_mul_lo_u32 v15, v15, s52
	v_add3_u32 v15, 0, v15, v14
	ds_read_b64_tr_b16 v[122:123], v15
	ds_read_b64_tr_b16 v[124:125], v15 offset:2112
	s_and_b64 vcc, exec, s[18:19]
	s_waitcnt lgkmcnt(9)
	v_mfma_f32_32x32x16_bf16 v[66:81], v[8:11], v[98:101], v[66:81]
	s_cbranch_vccnz .LBB0_1610
	v_mfma_f32_32x32x16_bf16 v[18:33], v[8:11], v[2:5], v[18:33]
.LBB0_1610:
	s_and_b64 vcc, exec, s[20:21]
	s_waitcnt lgkmcnt(6)
	v_mfma_f32_32x32x16_bf16 v[66:81], v[102:105], v[106:109], v[66:81]
	s_cbranch_vccnz .LBB0_1612
	v_mfma_f32_32x32x16_bf16 v[18:33], v[102:105], v[2:5], v[18:33]
.LBB0_1612:
	s_and_b64 vcc, exec, s[22:23]
	s_waitcnt lgkmcnt(3)
	v_mfma_f32_32x32x16_bf16 v[66:81], v[110:113], v[114:117], v[66:81]
	s_cbranch_vccnz .LBB0_1614
	v_mfma_f32_32x32x16_bf16 v[18:33], v[110:113], v[2:5], v[18:33]
.LBB0_1614:
	s_and_b64 vcc, exec, s[24:25]
	s_waitcnt lgkmcnt(0)
	v_mfma_f32_32x32x16_bf16 v[66:81], v[118:121], v[122:125], v[66:81]
	s_cbranch_vccnz .LBB0_1616
	v_mfma_f32_32x32x16_bf16 v[18:33], v[118:121], v[2:5], v[18:33]

.LBB0_1630:
	v_mov_b32_e32 v3, v229
	v_mov_b32_e32 v5, s80
	v_and_b32_e32 v4, 31, v3
	v_cmp_eq_u32_e32 vcc, 2, v4
	v_mad_u32_u24 v6, v4, s88, v5
	v_ashrrev_i32_e32 v4, 2, v3
	v_and_b32_e32 v13, -8, v4
	v_bfe_u32 v12, v3, 2, 2
	v_and_b32_e32 v4, 16, v3
	v_lshlrev_b32_e32 v3, 2, v3
	v_and_b32_e32 v3, 12, v3
	v_or3_b32 v3, v4, v3, s30
	v_lshlrev_b32_e32 v14, 1, v3
	v_lshl_add_u32 v3, v13, 1, v6
	ds_read_b128 v[8:11], v3
	v_or_b32_e32 v3, v13, v12
	v_mul_lo_u32 v3, v3, s52
	v_add3_u32 v3, 0, v3, v14
	ds_read_b64_tr_b16 v[98:99], v3
	ds_read_b64_tr_b16 v[100:101], v3 offset:2112
	v_add_u32_e32 v15, 16, v13
	v_lshl_add_u32 v102, v15, 1, v6
	ds_read_b128 v[102:105], v102
	v_or_b32_e32 v15, v15, v12
	v_mul_lo_u32 v15, v15, s52
	v_add3_u32 v15, 0, v15, v14
	ds_read_b64_tr_b16 v[106:107], v15
	ds_read_b64_tr_b16 v[108:109], v15 offset:2112
	v_add_u32_e32 v15, 32, v13
	v_lshl_add_u32 v110, v15, 1, v6
	ds_read_b128 v[110:113], v110
	v_or_b32_e32 v15, v15, v12
	v_mul_lo_u32 v15, v15, s52
	v_add3_u32 v15, 0, v15, v14
	ds_read_b64_tr_b16 v[114:115], v15
	ds_read_b64_tr_b16 v[116:117], v15 offset:2112
	v_add_u32_e32 v15, 48, v13
	v_lshl_add_u32 v118, v15, 1, v6
	ds_read_b128 v[118:121], v118
	v_or_b32_e32 v15, v15, v12
	v_mul_lo_u32 v15, v15, s52
	v_add3_u32 v15, 0, v15, v14
	ds_read_b64_tr_b16 v[122:123], v15
	ds_read_b64_tr_b16 v[124:125], v15 offset:2112
	s_waitcnt lgkmcnt(9)
	v_mfma_f32_32x32x16_bf16 v[50:65], v[8:11], v[98:101], v[50:65]
	v_cndmask_b32_e32 v2, 0, v242, vcc
	v_mov_b32_e32 v3, v2
	v_mov_b32_e32 v4, v2
	v_mov_b32_e32 v5, v2
	s_and_b64 vcc, exec, s[10:11]
	s_cbranch_vccnz .LBB0_1632
	v_mfma_f32_32x32x16_bf16 v[18:33], v[8:11], v[2:5], v[18:33]
.LBB0_1632:
	v_add_u32_e32 v15, 64, v13
	v_lshl_add_u32 v8, v15, 1, v6
	ds_read_b128 v[8:11], v8
	v_or_b32_e32 v15, v15, v12
	v_mul_lo_u32 v15, v15, s52
	v_add3_u32 v15, 0, v15, v14
	ds_read_b64_tr_b16 v[98:99], v15
	ds_read_b64_tr_b16 v[100:101], v15 offset:2112
	s_and_b64 vcc, exec, s[12:13]
	s_waitcnt lgkmcnt(9)
	v_mfma_f32_32x32x16_bf16 v[50:65], v[102:105], v[106:109], v[50:65]
	s_cbranch_vccnz .LBB0_1634
	v_mfma_f32_32x32x16_bf16 v[18:33], v[102:105], v[2:5], v[18:33]
.LBB0_1634:
	v_add_u32_e32 v15, 80, v13
	v_lshl_add_u32 v102, v15, 1, v6
	ds_read_b128 v[102:105], v102
	v_or_b32_e32 v15, v15, v12
	v_mul_lo_u32 v15, v15, s52
	v_add3_u32 v15, 0, v15, v14
	ds_read_b64_tr_b16 v[106:107], v15
	ds_read_b64_tr_b16 v[108:109], v15 offset:2112
	s_and_b64 vcc, exec, s[14:15]
	s_waitcnt lgkmcnt(9)
	v_mfma_f32_32x32x16_bf16 v[50:65], v[110:113], v[114:117], v[50:65]
	s_cbranch_vccnz .LBB0_1636
	v_mfma_f32_32x32x16_bf16 v[18:33], v[110:113], v[2:5], v[18:33]
.LBB0_1636:
	v_add_u32_e32 v15, 96, v13
	v_lshl_add_u32 v110, v15, 1, v6
	ds_read_b128 v[110:113], v110
	v_or_b32_e32 v15, v15, v12
	v_mul_lo_u32 v15, v15, s52
	v_add3_u32 v15, 0, v15, v14
	ds_read_b64_tr_b16 v[114:115], v15
	ds_read_b64_tr_b16 v[116:117], v15 offset:2112
	s_and_b64 vcc, exec, s[16:17]
	s_waitcnt lgkmcnt(9)
	v_mfma_f32_32x32x16_bf16 v[50:65], v[118:121], v[122:125], v[50:65]
	s_cbranch_vccnz .LBB0_1638
	v_mfma_f32_32x32x16_bf16 v[18:33], v[118:121], v[2:5], v[18:33]
.LBB0_1638:
	v_add_u32_e32 v15, 112, v13
	v_lshl_add_u32 v118, v15, 1, v6
	ds_read_b128 v[118:121], v118
	v_or_b32_e32 v15, v15, v12
	v_mul_lo_u32 v15, v15, s52
	v_add3_u32 v15, 0, v15, v14
	ds_read_b64_tr_b16 v[122:123], v15
	ds_read_b64_tr_b16 v[124:125], v15 offset:2112
	s_and_b64 vcc, exec, s[18:19]
	s_waitcnt lgkmcnt(9)
	v_mfma_f32_32x32x16_bf16 v[50:65], v[8:11], v[98:101], v[50:65]
	s_cbranch_vccnz .LBB0_1640
	v_mfma_f32_32x32x16_bf16 v[18:33], v[8:11], v[2:5], v[18:33]
.LBB0_1640:
	s_and_b64 vcc, exec, s[20:21]
	s_waitcnt lgkmcnt(6)
	v_mfma_f32_32x32x16_bf16 v[50:65], v[102:105], v[106:109], v[50:65]
	s_cbranch_vccnz .LBB0_1642
	v_mfma_f32_32x32x16_bf16 v[18:33], v[102:105], v[2:5], v[18:33]
.LBB0_1642:
	s_and_b64 vcc, exec, s[22:23]
	s_waitcnt lgkmcnt(3)
	v_mfma_f32_32x32x16_bf16 v[50:65], v[110:113], v[114:117], v[50:65]
	s_cbranch_vccnz .LBB0_1644
	v_mfma_f32_32x32x16_bf16 v[18:33], v[110:113], v[2:5], v[18:33]
.LBB0_1644:
	s_and_b64 vcc, exec, s[24:25]
	s_waitcnt lgkmcnt(0)
	v_mfma_f32_32x32x16_bf16 v[50:65], v[118:121], v[122:125], v[50:65]
	s_cbranch_vccnz .LBB0_1646
	v_mfma_f32_32x32x16_bf16 v[18:33], v[118:121], v[2:5], v[18:33]
.LBB0_1646:
	v_mov_b32_e32 v3, v229
	s_barrier
	v_mov_b32_e32 v5, s91
	v_and_b32_e32 v4, 31, v3
	v_cmp_eq_u32_e32 vcc, 3, v4
	v_mad_u32_u24 v6, v4, s88, v5
	v_ashrrev_i32_e32 v4, 2, v3
	v_and_b32_e32 v13, -8, v4
	v_bfe_u32 v12, v3, 2, 2
	v_and_b32_e32 v4, 16, v3
	v_lshlrev_b32_e32 v3, 2, v3
	v_and_b32_e32 v3, 12, v3
	v_or3_b32 v3, v4, v3, s30
	v_lshlrev_b32_e32 v14, 1, v3
	v_lshl_add_u32 v3, v13, 1, v6
	ds_read_b128 v[8:11], v3
	v_or_b32_e32 v3, v13, v12
	v_mul_lo_u32 v3, v3, s52
	v_add3_u32 v3, 0, v3, v14
	ds_read_b64_tr_b16 v[98:99], v3
	ds_read_b64_tr_b16 v[100:101], v3 offset:2112
	v_add_u32_e32 v15, 16, v13
	v_lshl_add_u32 v102, v15, 1, v6
	ds_read_b128 v[102:105], v102
	v_or_b32_e32 v15, v15, v12
	v_mul_lo_u32 v15, v15, s52
	v_add3_u32 v15, 0, v15, v14
	ds_read_b64_tr_b16 v[106:107], v15
	ds_read_b64_tr_b16 v[108:109], v15 offset:2112
	v_add_u32_e32 v15, 32, v13
	v_lshl_add_u32 v110, v15, 1, v6
	ds_read_b128 v[110:113], v110
	v_or_b32_e32 v15, v15, v12
	v_mul_lo_u32 v15, v15, s52
	v_add3_u32 v15, 0, v15, v14
	ds_read_b64_tr_b16 v[114:115], v15
	ds_read_b64_tr_b16 v[116:117], v15 offset:2112
	v_add_u32_e32 v15, 48, v13
	v_lshl_add_u32 v118, v15, 1, v6
	ds_read_b128 v[118:121], v118
	v_or_b32_e32 v15, v15, v12
	v_mul_lo_u32 v15, v15, s52
	v_add3_u32 v15, 0, v15, v14
	ds_read_b64_tr_b16 v[122:123], v15
	ds_read_b64_tr_b16 v[124:125], v15 offset:2112
	s_waitcnt lgkmcnt(9)
	v_mfma_f32_32x32x16_bf16 v[34:49], v[8:11], v[98:101], v[34:49]
	v_cndmask_b32_e32 v2, 0, v242, vcc
	v_mov_b32_e32 v3, v2
	v_mov_b32_e32 v4, v2
	v_mov_b32_e32 v5, v2
	s_and_b64 vcc, exec, s[10:11]
	s_cbranch_vccnz .LBB0_1648
	v_mfma_f32_32x32x16_bf16 v[18:33], v[8:11], v[2:5], v[18:33]
.LBB0_1648:
	v_add_u32_e32 v15, 64, v13
	v_lshl_add_u32 v8, v15, 1, v6
	ds_read_b128 v[8:11], v8
	v_or_b32_e32 v15, v15, v12
	v_mul_lo_u32 v15, v15, s52
	v_add3_u32 v15, 0, v15, v14
	ds_read_b64_tr_b16 v[98:99], v15
	ds_read_b64_tr_b16 v[100:101], v15 offset:2112
	s_and_b64 vcc, exec, s[12:13]
	s_waitcnt lgkmcnt(9)
	v_mfma_f32_32x32x16_bf16 v[34:49], v[102:105], v[106:109], v[34:49]
	s_cbranch_vccnz .LBB0_1650
	v_mfma_f32_32x32x16_bf16 v[18:33], v[102:105], v[2:5], v[18:33]
.LBB0_1650:
	v_add_u32_e32 v15, 80, v13
	v_lshl_add_u32 v102, v15, 1, v6
	ds_read_b128 v[102:105], v102
	v_or_b32_e32 v15, v15, v12
	v_mul_lo_u32 v15, v15, s52
	v_add3_u32 v15, 0, v15, v14
	ds_read_b64_tr_b16 v[106:107], v15
	ds_read_b64_tr_b16 v[108:109], v15 offset:2112
	s_and_b64 vcc, exec, s[14:15]
	s_waitcnt lgkmcnt(9)
	v_mfma_f32_32x32x16_bf16 v[34:49], v[110:113], v[114:117], v[34:49]
	s_cbranch_vccnz .LBB0_1652
	v_mfma_f32_32x32x16_bf16 v[18:33], v[110:113], v[2:5], v[18:33]
.LBB0_1652:
	v_add_u32_e32 v15, 96, v13
	v_lshl_add_u32 v110, v15, 1, v6
	ds_read_b128 v[110:113], v110
	v_or_b32_e32 v15, v15, v12
	v_mul_lo_u32 v15, v15, s52
	v_add3_u32 v15, 0, v15, v14
	ds_read_b64_tr_b16 v[114:115], v15
	ds_read_b64_tr_b16 v[116:117], v15 offset:2112
	s_and_b64 vcc, exec, s[16:17]
	s_waitcnt lgkmcnt(9)
	v_mfma_f32_32x32x16_bf16 v[34:49], v[118:121], v[122:125], v[34:49]
	s_cbranch_vccnz .LBB0_1654
	v_mfma_f32_32x32x16_bf16 v[18:33], v[118:121], v[2:5], v[18:33]
.LBB0_1654:
	v_add_u32_e32 v15, 112, v13
	v_lshl_add_u32 v118, v15, 1, v6
	ds_read_b128 v[118:121], v118
	v_or_b32_e32 v15, v15, v12
	v_mul_lo_u32 v15, v15, s52
	v_add3_u32 v15, 0, v15, v14
	ds_read_b64_tr_b16 v[122:123], v15
	ds_read_b64_tr_b16 v[124:125], v15 offset:2112
	s_and_b64 vcc, exec, s[18:19]
	s_waitcnt lgkmcnt(9)
	v_mfma_f32_32x32x16_bf16 v[34:49], v[8:11], v[98:101], v[34:49]
	s_cbranch_vccnz .LBB0_1656
	v_mfma_f32_32x32x16_bf16 v[18:33], v[8:11], v[2:5], v[18:33]
.LBB0_1656:
	s_and_b64 vcc, exec, s[20:21]
	s_waitcnt lgkmcnt(6)
	v_mfma_f32_32x32x16_bf16 v[34:49], v[102:105], v[106:109], v[34:49]
	s_cbranch_vccnz .LBB0_1658
	v_mfma_f32_32x32x16_bf16 v[18:33], v[102:105], v[2:5], v[18:33]
.LBB0_1658:
	s_and_b64 vcc, exec, s[22:23]
	s_waitcnt lgkmcnt(3)
	v_mfma_f32_32x32x16_bf16 v[34:49], v[110:113], v[114:117], v[34:49]
	s_cbranch_vccnz .LBB0_1660
	v_mfma_f32_32x32x16_bf16 v[18:33], v[110:113], v[2:5], v[18:33]
.LBB0_1660:
	s_and_b64 vcc, exec, s[24:25]
	s_waitcnt lgkmcnt(0)
	v_mfma_f32_32x32x16_bf16 v[34:49], v[118:121], v[122:125], v[34:49]
	s_cbranch_vccnz .LBB0_1539
	v_mfma_f32_32x32x16_bf16 v[18:33], v[118:121], v[2:5], v[18:33]
	s_branch .LBB0_1539
